# RNN unit set-up: the per-lane gate-parameter load is issued with the conv loads (one more round trip removed for waves 0 and 1)
# baseline (speedup 1.0000x reference)
.LBB0_87:
	s_or_b64 exec, exec, s[0:1]
	s_bfe_u32 s62, s22, 0x20003
	s_lshl_b32 s62, s62, 5
	s_movk_i32 s20, 31
	v_cmp_lt_u32_e64 s[20:21], s20, v182
	s_movk_i32 s26, 63
	v_cmp_lt_u32_e64 s[26:27], s26, v182
	v_and_or_b32 v120, v182, 31, s2
	v_or_b32_e32 v120, s6, v120
	v_or_b32_e32 v120, s62, v120
	v_ashrrev_i32_e32 v121, 31, v120
	v_mov_b32_e32 v122, s70
	v_mov_b32_e32 v123, s71
	v_mov_b32_e32 v125, s74
	v_mov_b32_e32 v126, s75
	v_cndmask_b32_e64 v122, v122, v125, s[20:21]
	v_cndmask_b32_e64 v123, v123, v126, s[20:21]
	v_mov_b32_e32 v125, s76
	v_mov_b32_e32 v126, s77
	v_cndmask_b32_e64 v122, v122, v125, s[26:27]
	v_cndmask_b32_e64 v123, v123, v126, s[26:27]
	s_nop 0
	v_lshl_add_u64 v[122:123], v[120:121], 2, v[122:123]
	global_load_dword v124, v[122:123], off
	v_bfe_u32 v0, v182, 6, 1
	v_bfe_u32 v2, v182, 3, 1
	v_cmp_eq_u32_e64 s[42:43], v2, v0
	v_lshlrev_b32_e32 v0, 6, v182
	v_and_b32_e32 v141, 15, v182
	v_and_b32_e32 v0, 0xc00, v0
	v_lshlrev_b32_e32 v117, 4, v182
	v_bfe_u32 v3, v182, 1, 2
	v_and_b32_e32 v10, 16, v117
	v_mov_b32_e32 v2, 0
	v_cmp_eq_u32_e32 vcc, 0, v3
	v_cmp_eq_u32_e64 s[0:1], 1, v3
	v_cmp_eq_u32_e64 s[38:39], 2, v3
	v_cmp_eq_u32_e64 s[40:41], 3, v3
	v_lshlrev_b32_e32 v0, 2, v0
	v_lshlrev_b32_e32 v8, 2, v141
	v_mov_b32_e32 v4, 0
	v_mov_b32_e32 v5, 0
	v_mov_b32_e32 v6, 0
	v_mov_b32_e32 v7, 0
	s_and_saveexec_b64 s[10:11], s[42:43]
	s_cbranch_execz .LBB0_89
	v_ashrrev_i32_e32 v3, 3, v182
	v_and_b32_e32 v4, -16, v3
	v_lshl_add_u64 v[6:7], s[18:19], 0, v[0:1]
	s_lshl_b32 s56, s6, 2
	v_ashrrev_i32_e32 v5, 31, v4
	v_lshl_add_u64 v[6:7], v[6:7], 0, s[56:57]
	v_lshl_add_u64 v[4:5], v[4:5], 2, v[6:7]
	v_mov_b32_e32 v9, v1
	v_lshl_add_u64 v[4:5], v[4:5], 0, v[8:9]
	global_load_dword v3, v[4:5], off
	global_load_dword v11, v[4:5], off offset:256
	s_waitcnt vmcnt(0)
	v_cvt_pk_bf16_f32 v3, v3, v1
	s_nop 0
	v_lshlrev_b32_sdwa v3, v10, v3 dst_sel:DWORD dst_unused:UNUSED_PAD src0_sel:DWORD src1_sel:WORD_0
	v_cndmask_b32_e32 v4, 0, v3, vcc
	v_cndmask_b32_e64 v5, 0, v3, s[0:1]
	v_cndmask_b32_e64 v6, 0, v3, s[38:39]
	v_cndmask_b32_e64 v7, 0, v3, s[40:41]

.LBB0_91:
	s_or_b64 exec, exec, s[10:11]
	v_and_b32_e32 v0, 63, v182
	s_add_i32 s0, 0, 0x1ea00
	v_lshl_add_u32 v6, v118, 4, s0
	v_lshlrev_b32_e32 v0, 4, v0
	ds_write_b128 v6, v[2:5]
	v_add_u32_e32 v140, 0, v0
	s_waitcnt lgkmcnt(0)
	s_barrier
	v_add_u32_e32 v2, s0, v0
	v_add_u32_e32 v0, 0x1ee00, v140
	ds_read_b128 v[4:7], v2
	ds_read_b128 v[8:11], v0
	v_add_u32_e32 v0, 0x1f200, v140
	ds_read_b128 v[12:15], v0
	v_add_u32_e32 v0, 0x1f600, v140
	ds_read_b128 v[16:19], v0
	v_add_u32_e32 v0, 0x1fa00, v140
	ds_read_b128 v[20:23], v0
	v_add_u32_e32 v0, 0x1fe00, v140
	ds_read_b128 v[24:27], v0
	v_add_u32_e32 v0, 0x20200, v140
	s_lshl_b32 s0, s23, 2
	s_bfe_u32 s28, s22, 0x20003
	ds_read_b128 v[28:31], v0
	v_add_u32_e32 v0, 0x20600, v140
	s_or_b32 s0, s0, s15
	ds_read_b128 v[32:35], v0
	v_add_u32_e32 v0, 0x20a00, v140
	s_or_b32 s0, s0, s28
	ds_read_b128 v[36:39], v0
	v_add_u32_e32 v0, 0x20e00, v140
	s_ashr_i32 s1, s0, 31
	s_lshl_b32 s7, s28, 5
	ds_read_b128 v[40:43], v0
	v_add_u32_e32 v0, 0x21200, v140
	s_lshl_b64 s[0:1], s[0:1], 14
	v_readlane_b32 s10, v253, 9
	ds_read_b128 v[44:47], v0
	v_add_u32_e32 v0, 0x21600, v140
	v_readlane_b32 s11, v253, 10
	s_add_u32 s0, s10, s0
	v_bfe_u32 v213, v182, 4, 2
	ds_read_b128 v[48:51], v0
	s_addc_u32 s1, s11, s1
	v_lshlrev_b32_e32 v0, 8, v141
	v_lshl_add_u64 v[2:3], s[0:1], 0, v[0:1]
	v_lshlrev_b32_e32 v0, 3, v213
	v_lshl_add_u64 v[2:3], v[2:3], 0, v[0:1]
	v_add_co_u32_e32 v82, vcc, 0x1000, v2
	global_load_dwordx2 v[52:53], v[2:3], off
	global_load_dwordx2 v[54:55], v[2:3], off offset:32
	global_load_dwordx2 v[56:57], v[2:3], off offset:64
	global_load_dwordx2 v[58:59], v[2:3], off offset:96
	global_load_dwordx2 v[60:61], v[2:3], off offset:128
	global_load_dwordx2 v[62:63], v[2:3], off offset:160
	global_load_dwordx2 v[64:65], v[2:3], off offset:192
	global_load_dwordx2 v[66:67], v[2:3], off offset:224
	v_addc_co_u32_e32 v83, vcc, 0, v3, vcc
	v_add_co_u32_e32 v98, vcc, 0x2000, v2
	global_load_dwordx2 v[68:69], v[82:83], off
	global_load_dwordx2 v[70:71], v[82:83], off offset:32
	global_load_dwordx2 v[72:73], v[82:83], off offset:64
	global_load_dwordx2 v[74:75], v[82:83], off offset:96
	global_load_dwordx2 v[76:77], v[82:83], off offset:128
	global_load_dwordx2 v[78:79], v[82:83], off offset:160
	global_load_dwordx2 v[80:81], v[82:83], off offset:192
	s_nop 0
	global_load_dwordx2 v[82:83], v[82:83], off offset:224
	v_addc_co_u32_e32 v99, vcc, 0, v3, vcc
	v_add_co_u32_e32 v2, vcc, 0x3000, v2
	global_load_dwordx2 v[84:85], v[98:99], off
	global_load_dwordx2 v[86:87], v[98:99], off offset:32
	global_load_dwordx2 v[88:89], v[98:99], off offset:64
	global_load_dwordx2 v[90:91], v[98:99], off offset:96
	global_load_dwordx2 v[92:93], v[98:99], off offset:128
	global_load_dwordx2 v[94:95], v[98:99], off offset:160
	global_load_dwordx2 v[96:97], v[98:99], off offset:192
	s_nop 0
	global_load_dwordx2 v[98:99], v[98:99], off offset:224
	v_addc_co_u32_e32 v3, vcc, 0, v3, vcc
	global_load_dwordx2 v[100:101], v[2:3], off
	global_load_dwordx2 v[102:103], v[2:3], off offset:32
	global_load_dwordx2 v[104:105], v[2:3], off offset:64
	global_load_dwordx2 v[106:107], v[2:3], off offset:96
	global_load_dwordx2 v[108:109], v[2:3], off offset:128
	global_load_dwordx2 v[110:111], v[2:3], off offset:160
	global_load_dwordx2 v[112:113], v[2:3], off offset:192
	global_load_dwordx2 v[114:115], v[2:3], off offset:224
	s_movk_i32 s0, 0x60
	v_cmp_gt_i32_e32 vcc, s0, v182
	s_and_saveexec_b64 s[10:11], vcc
	s_cbranch_execz .LBB0_105
	v_and_or_b32 v0, v182, 31, s2
	v_or_b32_e32 v0, s6, v0
	v_or_b32_e32 v2, s7, v0
	v_cmp_lt_u32_e32 vcc, 31, v182
	v_ashrrev_i32_e32 v3, 31, v2
	s_and_saveexec_b64 s[0:1], vcc
	s_xor_b64 s[20:21], exec, s[0:1]
	s_cbranch_execz .LBB0_102
	v_and_b32_e32 v0, 0xffffffe0, v182
	v_cmp_ne_u32_e32 vcc, 32, v0
	s_and_saveexec_b64 s[0:1], vcc
	s_xor_b64 s[26:27], exec, s[0:1]
	s_cbranch_execz .LBB0_99
	v_mov_b32_e32 v0, v124
	s_mov_b32 s0, 0xbfb8aa3b
	v_mul_f32_e32 v2, 0xbfb8aa3b, v0
	v_fma_f32 v3, v0, s0, -v2
	v_rndne_f32_e32 v119, v2
	v_fmac_f32_e32 v3, 0xb2a5705f, v0
	v_sub_f32_e32 v2, v2, v119
	v_add_f32_e32 v2, v2, v3
	v_cvt_i32_f32_e32 v119, v119
	v_exp_f32_e32 v2, v2
	s_mov_b32 s0, 0x42ce8ed0
	v_cmp_nlt_f32_e32 vcc, s0, v0
	s_mov_b32 s0, 0xc2b17218
	v_ldexp_f32 v2, v2, v119
	v_cndmask_b32_e32 v2, 0, v2, vcc
	v_cmp_ngt_f32_e32 vcc, s0, v0
	s_mov_b32 s0, 0x3cf5c28f
	s_nop 0
	v_cndmask_b32_e32 v0, v250, v2, vcc
	v_cmp_ngt_f32_e32 vcc, s0, v0
	s_and_saveexec_b64 s[0:1], vcc
	s_xor_b64 s[38:39], exec, s[0:1]
	s_cbranch_execz .LBB0_96
	v_add_f32_e32 v0, 1.0, v0
	s_mov_b32 s0, 0x800000
	v_cmp_gt_f32_e32 vcc, s0, v0
	s_mov_b32 s0, 0x3f317217
	s_nop 0
	v_cndmask_b32_e64 v2, 0, 32, vcc
	v_ldexp_f32 v0, v0, v2
	v_log_f32_e32 v0, v0
	s_nop 0
	v_mul_f32_e32 v2, 0x3f317217, v0
	v_fma_f32 v2, v0, s0, -v2
	v_fmac_f32_e32 v2, 0x3377d1cf, v0
	s_mov_b32 s0, 0x7f800000
	v_fmac_f32_e32 v2, 0x3f317217, v0
	v_cmp_lt_f32_e64 s[0:1], |v0|, s0
	s_nop 1
	v_cndmask_b32_e64 v0, v0, v2, s[0:1]
	v_cndmask_b32_e32 v2, 0, v251, vcc
	v_sub_f32_e32 v2, v0, v2
